# m5 plus G1: odd XCDs run the fp8 half of the input projection first (de-phases epilogue store bursts and operand streams across XCDs)
# speedup vs baseline: 1.0174x; 1.0063x over previous
;     __device__ __forceinline__ bool next(int i, Unit& u) const { if (i > 0) return false; return base.next(round, u); }
; #define PG8_STA(bufoff, T_, h) PG8_STAGE(bufoff, T_##_a + ((h) ? T_##_ha : 0), T_##_ha, T_##_s2, voffA, voffA2)
; #define PG8_STB(bufoff, T_, h) PG8_STAGE(bufoff, T_##_b + ((h) ? T_##_hb : 0), T_##_hb, false, voffB, voffB)
; #define PG8_WAIT_V(n) asm volatile("s_waitcnt vmcnt(" #n ")" ::: "memory")
; #define PG8_BAR __builtin_amdgcn_s_barrier()
; template <class Epi, class Sched, bool ALIGN_EPI = false, bool SP2 = true>
; __device__ __forceinline__ void gemm_phase(PG8_LAS unsigned char* lds, const Gemm g, const Sched& S, const Epi& E, int wid) {
;     ...
;     Unit cur, nxt; int ui = 0;
;     if (!S.next(0, cur)) return;
;     constexpr bool ZC = Epi::ZC;
;     f32x4 acc[2][2][4][2];
;     if constexpr (!ZC) {
; #pragma unroll
;     for (int a = 0; a < 2; ++a)
; #pragma unroll
;         for (int b = 0; b < 2; ++b)
; #pragma unroll
;             for (int m = 0; m < 4; ++m)
; #pragma unroll
;                 for (int n = 0; n < 2; ++n) acc[a][b][m][n] = (f32x4){0.f, 0.f, 0.f, 0.f};
;     }
;     i32x8 At[4], B0[2], B1[2];
;     S.a_ready(cur);
;     { PG8_KT(k0, 0, cur, cur); PG8_KT(k1, 1, cur, cur);
;       PG8_STB(PG8_SB(0, 0), k0, 0); PG8_STB(PG8_SB(0, 1), k0, 1); PG8_STA(PG8_SA(0, 0), k0, 0); PG8_STA(PG8_SA(0, 1), k0, 1);
;       if (wr == 1) PG8_BAR;
;       PG8_WAIT_V(2); PG8_BAR;
;       PG8_STB(PG8_SB(1, 0), k1, 0); PG8_STA(PG8_SA(1, 0), k1, 0); PG8_STB(PG8_SB(1, 1), k1, 1);
;       PG8_WAIT_V(6); PG8_BAR; }
; __global__ void __launch_bounds__(NWAVES * 64, 2) mk_fwd(Args args) {
;     ...
;         G1_BF16(); G1_FP8();
.LBB0_358:
	v_readlane_b32 s99, v254, 2
	s_nop 1
	s_bfe_u32 s99, s99, 0x10000
	s_xor_b32 s99, s99, 1
	s_lshl_b32 s99, s99, 1
	s_cmp_lt_i32 s94, 2
	s_cselect_b64 s[0:1], -1, 0
	s_cmp_gt_i32 s95, 1
	s_cselect_b64 s[4:5], -1, 0
	s_and_b64 s[0:1], s[0:1], s[4:5]
	s_andn2_b64 vcc, exec, s[0:1]
	s_cbranch_vccnz .LBB0_500
.Lg1_redo:
	v_readlane_b32 s0, v254, 2
	s_cmpk_lt_i32 s0, 0x700
	s_cselect_b64 s[4:5], -1, 0
	s_cmpk_gt_i32 s0, 0x6ff
	v_mbcnt_lo_u32_b32 v0, -1, 0
	v_mbcnt_hi_u32_b32 v0, -1, v0
	s_cbranch_scc1 .LBB0_361
	v_readlane_b32 s2, v254, 2
	s_ashr_i32 s0, s2, 31
	s_lshr_b32 s0, s0, 29
	s_add_i32 s0, s2, s0
	s_ashr_i32 s1, s0, 3
	s_and_b32 s0, s0, -8
	s_sub_i32 s0, s2, s0
	s_cmp_lt_i32 s0, 0
	s_movk_i32 s2, 0xe1
	s_cselect_b32 s2, s2, 0xe0
	s_mul_i32 s0, s0, s2
	s_add_i32 s0, s0, s1
	s_mul_hi_i32 s1, s0, 0x92492493
	s_add_i32 s1, s1, s0
	s_lshr_b32 s2, s1, 31
	s_ashr_i32 s1, s1, 4
	s_add_i32 s1, s1, s2
	s_lshl_b32 s2, s1, 1
	s_mul_i32 s1, s1, 28
	s_sub_i32 s0, s0, s1
	s_bfe_u32 s1, s0, 0x10007
	s_add_i32 s1, s0, s1
	s_bfe_i32 s6, s1, 0x80000
	s_and_b32 s1, s1, 0xfe
	s_sub_i32 s0, s0, s1
	s_sext_i32_i16 s6, s6
	s_sext_i32_i8 s0, s0
	s_add_i32 s66, s2, s0
	s_ashr_i32 s64, s6, 1
.LBB0_361:
	s_add_u32 s0, s10, 0x1880000
	s_addc_u32 s1, s11, 0
	v_writelane_b32 v254, s0, 44
	s_lshr_b32 s8, s48, 8
	s_bfe_u32 s19, s48, 0x20006
	v_writelane_b32 v254, s1, 45
	v_cndmask_b32_e64 v1, 0, 1, s[4:5]
	v_readlane_b32 s0, v254, 4
	v_writelane_b32 v254, s94, 46
	s_lshl_b32 s6, s0, 10
	s_lshl_b32 s59, s8, 6
	v_writelane_b32 v254, s95, 47
	s_lshl_b32 s13, s8, 13
	s_lshl_b32 s61, s19, 5
	v_cmp_ne_u32_e64 s[14:15], 1, v1
	s_andn2_b64 vcc, exec, s[4:5]
	s_lshl_b32 s18, s19, 12
	v_writelane_b32 v254, s52, 48
	s_cmp_eq_u32 s99, 0
	s_cbranch_scc1 .LBB0_399
	s_cbranch_vccnz .LBB0_399
	v_lshlrev_b32_e32 v1, 4, v0
	v_add_u32_e32 v2, s6, v1
	v_ashrrev_i32_e32 v3, 31, v2
	v_lshrrev_b32_e32 v3, 22, v3
	v_add_u32_e32 v3, v2, v3
	v_ashrrev_i32_e32 v3, 10, v3
	v_mul_i32_i24_e32 v4, 0x400, v3
	v_sub_u32_e32 v2, v2, v4
	v_lshrrev_b32_e32 v4, 4, v2
	v_bitop3_b32 v2, v4, v2, 32 bitop3:0x6c
	v_ashrrev_i32_e32 v5, 31, v2
	s_add_u32 s21, s10, 0x18000000
	v_lshrrev_b32_e32 v5, 26, v5
	s_addc_u32 s22, s11, 0
	v_lshlrev_b32_e32 v4, 3, v3
	v_add_u32_e32 v5, v2, v5
	s_add_u32 s23, s10, 0x100000
	v_and_b32_e32 v4, -16, v4
	v_ashrrev_i32_e32 v6, 6, v5
	s_addc_u32 s26, s11, 0
	v_add_u32_e32 v4, v6, v4
	v_and_b32_e32 v6, 3, v6
	s_mov_b32 s0, 0x1fffe0
	s_ashr_i32 s67, s66, 31
	v_and_or_b32 v6, v4, s0, v6
	s_lshl_b64 s[0:1], s[66:67], 19
	v_and_b32_e32 v5, 0xc0, v5
	s_add_u32 s16, s21, s0
	v_sub_u32_e32 v2, v2, v5
	v_mov_b32_e32 v5, 1
	s_addc_u32 s17, s22, s1
	s_ashr_i32 s65, s64, 31
	v_lshlrev_b32_e32 v3, 5, v3
	v_ashrrev_i16_sdwa v2, v5, sext(v2) dst_sel:DWORD dst_unused:UNUSED_PAD src0_sel:DWORD src1_sel:BYTE_0
	v_lshlrev_b32_e32 v5, 1, v4
	v_lshrrev_b32_e32 v7, 2, v4
	s_lshl_b64 s[0:1], s[64:65], 19
	v_and_b32_e32 v3, 32, v3
	v_bfe_i32 v2, v2, 0, 16
	v_and_b32_e32 v5, 24, v5
	v_and_b32_e32 v7, 4, v7
	s_add_u32 s4, s23, s0
	v_or3_b32 v5, v6, v7, v5
	v_add_lshl_u32 v2, v3, v2, 1
	s_addc_u32 s5, s26, s1
	s_add_i32 s27, s6, 0
	v_lshl_add_u32 v179, v5, 11, v2
	s_add_i32 s33, s27, 0x10000
	s_mov_b32 s0, m0
	s_mov_b32 m0, s33
	s_nop 0
	global_load_lds_dwordx4 v179, s[4:5]
	s_mov_b32 m0, s0
	s_add_u32 s0, s4, 0x20000
	s_addc_u32 s1, s5, 0
	s_add_i32 s35, s27, 0x12000
	s_mov_b32 s2, m0
	s_mov_b32 m0, s35
	s_nop 0
	global_load_lds_dwordx4 v179, s[0:1]
	s_mov_b32 m0, s2
	s_add_u32 s0, s4, 0x40000
	s_addc_u32 s1, s5, 0
	s_add_i32 s38, s27, 0x14000
	s_mov_b32 s2, m0
	s_mov_b32 m0, s38
	s_nop 0
	global_load_lds_dwordx4 v179, s[0:1]
	s_mov_b32 m0, s2
	s_add_u32 s0, s4, 0x60000
	s_addc_u32 s1, s5, 0
	s_add_i32 s39, s27, 0x16000
	s_mov_b32 s2, m0
	s_mov_b32 m0, s39
	s_nop 0
	global_load_lds_dwordx4 v179, s[0:1]
	s_mov_b32 m0, s2
	v_lshl_add_u32 v178, v4, 11, v2
	s_mov_b32 s0, m0
	s_mov_b32 m0, s27
	s_nop 0
	global_load_lds_dwordx4 v178, s[16:17]
	s_mov_b32 m0, s0
	s_add_u32 s0, s16, 0x20000
	s_addc_u32 s1, s17, 0
	s_add_i32 s40, s27, 0x2000
	s_mov_b32 s2, m0
	s_mov_b32 m0, s40
	s_nop 0
	global_load_lds_dwordx4 v178, s[0:1]
	s_mov_b32 m0, s2
	s_add_u32 s0, s16, 0x40000
	s_addc_u32 s1, s17, 0
	s_add_i32 s41, s27, 0x4000
	s_mov_b32 s2, m0
	s_mov_b32 m0, s41
	s_nop 0
	global_load_lds_dwordx4 v178, s[0:1]
	s_mov_b32 m0, s2
	s_add_u32 s0, s16, 0x60000
	v_writelane_b32 v254, s14, 49
	s_addc_u32 s1, s17, 0
	s_add_i32 s48, s27, 0x6000
	v_writelane_b32 v254, s15, 50
	s_mov_b32 s2, m0
	s_mov_b32 m0, s48
	s_nop 0
	global_load_lds_dwordx4 v178, s[0:1]
	s_mov_b32 m0, s2
	s_cmp_lg_u32 s8, 1
	v_writelane_b32 v254, s6, 51
	s_cselect_b64 s[14:15], -1, 0
	s_mov_b32 s12, 0
	v_writelane_b32 v254, s8, 52
	s_and_b64 vcc, exec, s[14:15]
	s_cbranch_vccnz .LBB0_364
	s_barrier

;     __device__ __forceinline__ bool next(int i, Unit& u) const { if (i > 0) return false; return base.next(round, u); }
;     __host__ __device__ bool next(int i, Unit& u) const {
;         const long L = (long)i * G + c; if (L >= nwg) return false;
;         int wgid = (int)L; { const int q = nwg / NXCD, r = nwg % NXCD, xcd = wgid % NXCD, off = wgid / NXCD; wgid = (xcd < r ? xcd * (q + 1) : r * (q + 1) + (xcd - r) * q) + off; }
;         const int nig = wgm * nN, gid = wgid / nig, fm = gid * wgm, gsz = (nM - fm) < wgm ? (nM - fm) : wgm;
;         u.pm = fm + ((wgid % nig) % gsz); u.pn = (wgid % nig) / gsz; return true;
; __global__ void __launch_bounds__(NWAVES * 64, 2) mk_fwd(Args args) {
;     ...
;         G1_BF16(); G1_FP8();
.LBB0_399:
	s_cmp_eq_u32 s99, 1
	s_cbranch_scc1 .LBB0_444
	s_and_b64 vcc, exec, s[14:15]
	v_mbcnt_lo_u32_b32 v0, -1, 0
	v_mbcnt_hi_u32_b32 v0, -1, v0
	s_cbranch_vccnz .LBB0_402
	v_readlane_b32 s2, v254, 2
	s_ashr_i32 s0, s2, 31
	s_lshr_b32 s0, s0, 29
	s_add_i32 s0, s2, s0
	s_ashr_i32 s1, s0, 3
	s_and_b32 s0, s0, -8
	s_sub_i32 s0, s2, s0
	s_cmp_lt_i32 s0, 0
	s_movk_i32 s2, 0xe1
	s_cselect_b32 s2, s2, 0xe0
	s_mul_i32 s0, s0, s2
	s_add_i32 s0, s0, s1
	s_mul_hi_i32 s1, s0, 0x92492493
	s_add_i32 s1, s1, s0
	s_lshr_b32 s2, s1, 31
	s_ashr_i32 s1, s1, 4
	s_add_i32 s1, s1, s2
	s_lshl_b32 s2, s1, 1
	s_mul_i32 s1, s1, 28
	s_sub_i32 s0, s0, s1
	s_bfe_u32 s1, s0, 0x10007
	s_add_i32 s1, s0, s1
	s_bfe_i32 s4, s1, 0x80000
	s_and_b32 s1, s1, 0xfe
	s_sub_i32 s0, s0, s1
	s_sext_i32_i16 s4, s4
	s_sext_i32_i8 s0, s0
	s_add_i32 s64, s2, s0
	s_ashr_i32 s66, s4, 1
	s_and_b64 vcc, exec, s[14:15]
	s_cbranch_vccz .LBB0_403

; #define PG8_WAIT_V(n) asm volatile("s_waitcnt vmcnt(" #n ")" ::: "memory")
; #define PG8_BAR __builtin_amdgcn_s_barrier()
; #define GRID_BAR() do { if (N_LAUNCHES == 1) xcd_barrier(bar); } while (0)
; #define BOTH(k) (IN(k) && IN((k) + 1))
; template <class Epi, class Sched, bool ALIGN_EPI = false, bool SP2 = true>
; __device__ __forceinline__ void gemm_phase(PG8_LAS unsigned char* lds, const Gemm g, const Sched& S, const Epi& E, int wid) {
;     ...
;     PG8_WAIT_V(0);
;     if constexpr (!ALIGN_EPI) { if (wr == 0) PG8_BAR; }
;     PG8_BAR;
; __global__ void __launch_bounds__(NWAVES * 64, 2) mk_fwd(Args args) {
;     ...
;         G1_BF16(); G1_FP8();
;     ...
;         if (BOTH(1)) GRID_BAR();
.LBB0_444:
	s_waitcnt vmcnt(0)
	v_readlane_b32 s94, v254, 46
	v_readlane_b32 s48, v254, 11
	v_readlane_b32 s95, v254, 47
	v_readlane_b32 s52, v254, 48
	s_cmp_lg_u32 s99, 0
	s_cbranch_scc1 .Lg1_tail
	s_mov_b32 s99, 1
	s_barrier
	s_branch .Lg1_redo
.Lg1_tail:
	s_barrier
	s_cmp_lt_i32 s95, 3
	s_cbranch_scc1 .LBB0_500

; __global__ void __launch_bounds__(NWAVES * 64, 2) mk_fwd(Args args) {
	.amdhsa_kernel _Z6mk_fwd4Args
		.amdhsa_group_segment_fixed_size 0
		.amdhsa_private_segment_fixed_size 0
		.amdhsa_kernarg_size 424
		.amdhsa_user_sgpr_count 2
		.amdhsa_user_sgpr_dispatch_ptr 0
		.amdhsa_user_sgpr_queue_ptr 0
		.amdhsa_user_sgpr_kernarg_segment_ptr 1
		.amdhsa_user_sgpr_dispatch_id 0
		.amdhsa_user_sgpr_kernarg_preload_length 0
		.amdhsa_user_sgpr_kernarg_preload_offset 0
		.amdhsa_user_sgpr_private_segment_size 0
		.amdhsa_uses_dynamic_stack 0
		.amdhsa_enable_private_segment 0
		.amdhsa_system_sgpr_workgroup_id_x 1
		.amdhsa_system_sgpr_workgroup_id_y 0
		.amdhsa_system_sgpr_workgroup_id_z 0
		.amdhsa_system_sgpr_workgroup_info 0
		.amdhsa_system_vgpr_workitem_id 0
		.amdhsa_next_free_vgpr 256
		.amdhsa_next_free_sgpr 102
		.amdhsa_accum_offset 256
		.amdhsa_reserve_vcc 1
		.amdhsa_float_round_mode_32 0
		.amdhsa_float_round_mode_16_64 0
		.amdhsa_float_denorm_mode_32 3
		.amdhsa_float_denorm_mode_16_64 3
		.amdhsa_dx10_clamp 1
		.amdhsa_ieee_mode 1
		.amdhsa_fp16_overflow 0
		.amdhsa_tg_split 0
		.amdhsa_exception_fp_ieee_invalid_op 0
		.amdhsa_exception_fp_denorm_src 0
		.amdhsa_exception_fp_ieee_div_zero 0
		.amdhsa_exception_fp_ieee_overflow 0
		.amdhsa_exception_fp_ieee_underflow 0
		.amdhsa_exception_fp_ieee_inexact 0
		.amdhsa_exception_int_div_zero 0
	.end_amdhsa_kernel

; __global__ void __launch_bounds__(NWAVES * 64, 2) mk_fwd(Args args) {
amdhsa.kernels:
  - .agpr_count:     0
    .args:
      - .offset:         0
        .size:           168
        .value_kind:     by_value
      - .offset:         168
        .size:           4
        .value_kind:     hidden_block_count_x
      - .offset:         172
        .size:           4
        .value_kind:     hidden_block_count_y
      - .offset:         176
        .size:           4
        .value_kind:     hidden_block_count_z
      - .offset:         180
        .size:           2
        .value_kind:     hidden_group_size_x
      - .offset:         182
        .size:           2
        .value_kind:     hidden_group_size_y
      - .offset:         184
        .size:           2
        .value_kind:     hidden_group_size_z
      - .offset:         186
        .size:           2
        .value_kind:     hidden_remainder_x
      - .offset:         188
        .size:           2
        .value_kind:     hidden_remainder_y
      - .offset:         190
        .size:           2
        .value_kind:     hidden_remainder_z
      - .offset:         208
        .size:           8
        .value_kind:     hidden_global_offset_x
      - .offset:         216
        .size:           8
        .value_kind:     hidden_global_offset_y
      - .offset:         224
        .size:           8
        .value_kind:     hidden_global_offset_z
      - .offset:         232
        .size:           2
        .value_kind:     hidden_grid_dims
      - .offset:         288
        .size:           4
        .value_kind:     hidden_dynamic_lds_size
    .group_segment_fixed_size: 0
    .kernarg_segment_align: 8
    .kernarg_segment_size: 424
    .language:       OpenCL C
    .language_version:
      - 2
      - 0
    .max_flat_workgroup_size: 512
    .name:           _Z6mk_fwd4Args
    .private_segment_fixed_size: 0
    .sgpr_count:     108
    .sgpr_spill_count: 84
    .symbol:         _Z6mk_fwd4Args.kd
    .uniform_work_group_size: 1
    .uses_dynamic_stack: false
    .vgpr_count:     256
    .vgpr_spill_count: 0
    .wavefront_size: 64
